# PEER gather: odd rows loaded as dwordx4 at -4 bytes straight into the convert operand pairs (no staging moves)
# speedup vs baseline: 1.0069x; 1.0069x over previous
.LpA_hdr:
	v_ashrrev_i32_e32 v143, 31, v142
	v_lshlrev_b64 v[164:165], 11, v[142:143]
	v_lshl_add_u64 v[162:163], v[144:145], 0, v[164:165]
	global_load_dwordx4 v[2:5], v[162:163], off
	global_load_dwordx4 v[6:9], v[162:163], off offset:16
	v_lshlrev_b64 v[10:11], 9, v[142:143]
	v_lshl_or_b32 v10, v136, 2, v10
	v_lshl_add_u64 v[18:19], s[82:83], 0, v[10:11]
	v_lshl_add_u64 v[20:21], s[64:65], 0, v[10:11]
	global_load_dword v211, v[18:19], off
	global_load_dword v212, v[18:19], off offset:256
	global_load_dword v213, v[20:21], off
	global_load_dword v214, v[20:21], off offset:256
	s_mov_b32 s33, 0
	s_mov_b32 s34, 0
	v_mov_b32_e32 v180, 0
	v_mov_b32_e32 v181, v139
	v_mov_b32_e32 v178, 0
	v_mov_b32_e32 v179, v139
	v_mov_b32_e32 v176, 0
	v_mov_b32_e32 v177, v139
	v_mov_b32_e32 v174, 0
	v_mov_b32_e32 v175, v139
	v_mov_b32_e32 v172, 0
	v_mov_b32_e32 v173, v139
	v_mov_b32_e32 v170, 0
	v_mov_b32_e32 v171, v139
	v_mov_b32_e32 v168, 0
	v_mov_b32_e32 v169, v139
	v_mov_b32_e32 v166, 0
	v_mov_b32_e32 v167, v139
	s_waitcnt vmcnt(5)
	v_lshlrev_b32_e32 v10, 16, v2
	v_and_b32_e32 v11, 0xffff0000, v2
	v_lshlrev_b32_e32 v12, 16, v3
	v_and_b32_e32 v13, 0xffff0000, v3
	v_lshlrev_b32_e32 v2, 16, v4
	v_and_b32_e32 v3, 0xffff0000, v4
	v_lshlrev_b32_e32 v4, 16, v5
	v_and_b32_e32 v5, 0xffff0000, v5
	s_waitcnt vmcnt(4)
	v_lshlrev_b32_e32 v14, 16, v6
	v_and_b32_e32 v15, 0xffff0000, v6
	v_lshlrev_b32_e32 v16, 16, v7
	v_and_b32_e32 v17, 0xffff0000, v7
	v_lshlrev_b32_e32 v6, 16, v8
	v_and_b32_e32 v7, 0xffff0000, v8
	v_lshlrev_b32_e32 v8, 16, v9
	v_and_b32_e32 v9, 0xffff0000, v9
	ds_write_b128 v201, v[10:13]
	ds_write_b128 v201, v[2:5] offset:16
	ds_write_b128 v201, v[14:17] offset:32
	ds_write_b128 v201, v[6:9] offset:48
	s_nop 0
	s_nop 0
	s_nop 0
	s_nop 0
	v_and_b32_e32 v3, 64, v182
	ds_read_b32 v232, v137
	ds_read_b32 v233, v183
	ds_read_b32 v234, v184
	ds_read_b32 v235, v185
	ds_read_b32 v236, v186
	ds_read_b32 v237, v187
	ds_read_b32 v238, v188
	ds_read_b32 v239, v189
	ds_read_b32 v240, v190
	ds_read_b32 v241, v191
	ds_read_b32 v242, v192
	ds_read_b32 v243, v193
	ds_read_b32 v244, v194
	ds_read_b32 v245, v195
	ds_read_b32 v246, v196
	ds_read_b32 v247, v197
	v_xor_b32_e32 v2, 1, v182
	v_add_u32_e32 v4, 64, v3
	v_cmp_lt_i32_e64 s[2:3], v2, v4
	v_or_b32_e32 v231, v198, v3
	s_nop 0
	v_cndmask_b32_e64 v2, v182, v2, s[2:3]
	v_lshlrev_b32_e32 v205, 2, v2
	v_xor_b32_e32 v2, 2, v182
	v_cmp_lt_i32_e64 s[2:3], v2, v4
	s_nop 1
	v_cndmask_b32_e64 v2, v182, v2, s[2:3]
	v_lshlrev_b32_e32 v206, 2, v2
	v_xor_b32_e32 v2, 4, v182
	v_cmp_lt_i32_e64 s[2:3], v2, v4
	s_nop 1
	v_cndmask_b32_e64 v2, v182, v2, s[2:3]
	v_lshlrev_b32_e32 v207, 2, v2
	v_xor_b32_e32 v2, 8, v182
	v_cmp_lt_i32_e64 s[2:3], v2, v4
	s_nop 1
	v_cndmask_b32_e64 v2, v182, v2, s[2:3]
	v_lshlrev_b32_e32 v208, 2, v2
	v_xor_b32_e32 v2, 16, v182
	v_cmp_lt_i32_e64 s[2:3], v2, v4
	s_nop 1
	v_cndmask_b32_e64 v2, v182, v2, s[2:3]
	v_lshlrev_b32_e32 v209, 2, v2
	v_xor_b32_e32 v2, 32, v182
	v_cmp_lt_i32_e64 s[2:3], v2, v4
	s_nop 1
	v_cndmask_b32_e64 v2, v182, v2, s[2:3]
	v_lshlrev_b32_e32 v210, 2, v2
	s_waitcnt vmcnt(0)
	s_add_i32 s49, s33, 0
	v_readlane_b32 s40, v211, s49
	s_add_i32 s49, s33, 1
	v_readlane_b32 s41, v211, s49
	s_add_i32 s49, s33, 2
	v_readlane_b32 s42, v211, s49
	s_add_i32 s49, s33, 3
	v_readlane_b32 s43, v211, s49
	s_add_i32 s49, s33, 4
	v_readlane_b32 s44, v211, s49
	s_add_i32 s49, s33, 5
	v_readlane_b32 s45, v211, s49
	s_add_i32 s49, s33, 6
	v_readlane_b32 s46, v211, s49
	s_add_i32 s49, s33, 7
	v_readlane_b32 s47, v211, s49
	v_mad_u32_u24 v153, s41, v202, v138
	v_mad_u32_u24 v152, s40, v202, v138
	global_load_dwordx4 v[50:53], v153, s[78:79] offset:-4
	global_load_dwordx3 v[48:50], v152, s[78:79]
	v_mad_u32_u24 v155, s43, v202, v138
	v_mad_u32_u24 v154, s42, v202, v138
	global_load_dwordx4 v[56:59], v155, s[78:79] offset:-4
	global_load_dwordx3 v[54:56], v154, s[78:79]
	v_mad_u32_u24 v153, s45, v202, v138
	v_mad_u32_u24 v152, s44, v202, v138
	global_load_dwordx4 v[62:65], v153, s[78:79] offset:-4
	global_load_dwordx3 v[60:62], v152, s[78:79]
	v_mad_u32_u24 v155, s47, v202, v138
	v_mad_u32_u24 v154, s46, v202, v138
	global_load_dwordx4 v[78:81], v155, s[78:79] offset:-4
	global_load_dwordx3 v[76:78], v154, s[78:79]
	s_add_i32 s49, s33, 8
	v_readlane_b32 s40, v211, s49
	s_add_i32 s49, s33, 9
	v_readlane_b32 s41, v211, s49
	s_add_i32 s49, s33, 10
	v_readlane_b32 s42, v211, s49
	s_add_i32 s49, s33, 11
	v_readlane_b32 s43, v211, s49
	s_add_i32 s49, s33, 12
	v_readlane_b32 s44, v211, s49
	s_add_i32 s49, s33, 13
	v_readlane_b32 s45, v211, s49
	s_add_i32 s49, s33, 14
	v_readlane_b32 s46, v211, s49
	s_add_i32 s49, s33, 15
	v_readlane_b32 s47, v211, s49
	v_mad_u32_u24 v153, s41, v202, v138
	v_mad_u32_u24 v152, s40, v202, v138
	global_load_dwordx4 v[36:39], v153, s[78:79] offset:-4
	global_load_dwordx3 v[34:36], v152, s[78:79]
	v_mad_u32_u24 v155, s43, v202, v138
	v_mad_u32_u24 v154, s42, v202, v138
	global_load_dwordx4 v[68:71], v155, s[78:79] offset:-4
	global_load_dwordx3 v[66:68], v154, s[78:79]
	v_mad_u32_u24 v153, s45, v202, v138
	v_mad_u32_u24 v152, s44, v202, v138
	global_load_dwordx4 v[100:103], v153, s[78:79] offset:-4
	global_load_dwordx3 v[98:100], v152, s[78:79]
	v_mad_u32_u24 v155, s47, v202, v138
	v_mad_u32_u24 v154, s46, v202, v138
	global_load_dwordx4 v[132:135], v155, s[78:79] offset:-4
	global_load_dwordx3 v[130:132], v154, s[78:79]
.LpA_kb:
	s_waitcnt vmcnt(8)
	s_cmp_lt_u32 s34, 8
	s_cselect_b64 s[2:3], -1, 0
	s_waitcnt vmcnt(8)
	s_waitcnt lgkmcnt(0)
	v_cvt_scalef32_pk32_f32_fp6 v[2:33], v[48:53], 1.0
	v_pk_mul_f32 v[108:109], v[232:233], v[2:3]
	v_pk_mul_f32 v[110:111], v[232:233], v[18:19]
	v_pk_fma_f32 v[108:109], v[234:235], v[4:5], v[108:109]
	v_pk_fma_f32 v[110:111], v[234:235], v[20:21], v[110:111]
	v_pk_fma_f32 v[108:109], v[236:237], v[6:7], v[108:109]
	v_pk_fma_f32 v[110:111], v[236:237], v[22:23], v[110:111]
	v_pk_fma_f32 v[108:109], v[238:239], v[8:9], v[108:109]
	v_pk_fma_f32 v[110:111], v[238:239], v[24:25], v[110:111]
	v_pk_fma_f32 v[108:109], v[240:241], v[10:11], v[108:109]
	v_pk_fma_f32 v[110:111], v[240:241], v[26:27], v[110:111]
	v_pk_fma_f32 v[108:109], v[242:243], v[12:13], v[108:109]
	v_pk_fma_f32 v[110:111], v[242:243], v[28:29], v[110:111]
	v_pk_fma_f32 v[108:109], v[244:245], v[14:15], v[108:109]
	v_pk_fma_f32 v[110:111], v[244:245], v[30:31], v[110:111]
	v_pk_fma_f32 v[108:109], v[246:247], v[16:17], v[108:109]
	v_pk_fma_f32 v[110:111], v[246:247], v[32:33], v[110:111]
	s_nop 0
	v_add_f32_e32 v112, v108, v109
	v_add_f32_e32 v113, v110, v111
	v_cvt_scalef32_pk32_f32_fp6 v[2:33], v[54:59], 1.0
	v_pk_mul_f32 v[108:109], v[232:233], v[2:3]
	v_pk_mul_f32 v[110:111], v[232:233], v[18:19]
	v_pk_fma_f32 v[108:109], v[234:235], v[4:5], v[108:109]
	v_pk_fma_f32 v[110:111], v[234:235], v[20:21], v[110:111]
	v_pk_fma_f32 v[108:109], v[236:237], v[6:7], v[108:109]
	v_pk_fma_f32 v[110:111], v[236:237], v[22:23], v[110:111]
	v_pk_fma_f32 v[108:109], v[238:239], v[8:9], v[108:109]
	v_pk_fma_f32 v[110:111], v[238:239], v[24:25], v[110:111]
	v_pk_fma_f32 v[108:109], v[240:241], v[10:11], v[108:109]
	v_pk_fma_f32 v[110:111], v[240:241], v[26:27], v[110:111]
	v_pk_fma_f32 v[108:109], v[242:243], v[12:13], v[108:109]
	v_pk_fma_f32 v[110:111], v[242:243], v[28:29], v[110:111]
	v_pk_fma_f32 v[108:109], v[244:245], v[14:15], v[108:109]
	v_pk_fma_f32 v[110:111], v[244:245], v[30:31], v[110:111]
	v_pk_fma_f32 v[108:109], v[246:247], v[16:17], v[108:109]
	v_pk_fma_f32 v[110:111], v[246:247], v[32:33], v[110:111]
	s_nop 0
	v_add_f32_e32 v114, v108, v109
	v_add_f32_e32 v115, v110, v111
	v_cvt_scalef32_pk32_f32_fp6 v[2:33], v[60:65], 1.0
	v_pk_mul_f32 v[108:109], v[232:233], v[2:3]
	v_pk_mul_f32 v[110:111], v[232:233], v[18:19]
	v_pk_fma_f32 v[108:109], v[234:235], v[4:5], v[108:109]
	v_pk_fma_f32 v[110:111], v[234:235], v[20:21], v[110:111]
	v_pk_fma_f32 v[108:109], v[236:237], v[6:7], v[108:109]
	v_pk_fma_f32 v[110:111], v[236:237], v[22:23], v[110:111]
	v_pk_fma_f32 v[108:109], v[238:239], v[8:9], v[108:109]
	v_pk_fma_f32 v[110:111], v[238:239], v[24:25], v[110:111]
	v_pk_fma_f32 v[108:109], v[240:241], v[10:11], v[108:109]
	v_pk_fma_f32 v[110:111], v[240:241], v[26:27], v[110:111]
	v_pk_fma_f32 v[108:109], v[242:243], v[12:13], v[108:109]
	v_pk_fma_f32 v[110:111], v[242:243], v[28:29], v[110:111]
	v_pk_fma_f32 v[108:109], v[244:245], v[14:15], v[108:109]
	v_pk_fma_f32 v[110:111], v[244:245], v[30:31], v[110:111]
	v_pk_fma_f32 v[108:109], v[246:247], v[16:17], v[108:109]
	v_pk_fma_f32 v[110:111], v[246:247], v[32:33], v[110:111]
	s_nop 0
	v_add_f32_e32 v116, v108, v109
	v_add_f32_e32 v117, v110, v111
	v_cvt_scalef32_pk32_f32_fp6 v[2:33], v[76:81], 1.0
	v_pk_mul_f32 v[108:109], v[232:233], v[2:3]
	v_pk_mul_f32 v[110:111], v[232:233], v[18:19]
	v_pk_fma_f32 v[108:109], v[234:235], v[4:5], v[108:109]
	v_pk_fma_f32 v[110:111], v[234:235], v[20:21], v[110:111]
	v_pk_fma_f32 v[108:109], v[236:237], v[6:7], v[108:109]
	v_pk_fma_f32 v[110:111], v[236:237], v[22:23], v[110:111]
	v_pk_fma_f32 v[108:109], v[238:239], v[8:9], v[108:109]
	v_pk_fma_f32 v[110:111], v[238:239], v[24:25], v[110:111]
	v_pk_fma_f32 v[108:109], v[240:241], v[10:11], v[108:109]
	v_pk_fma_f32 v[110:111], v[240:241], v[26:27], v[110:111]
	v_pk_fma_f32 v[108:109], v[242:243], v[12:13], v[108:109]
	v_pk_fma_f32 v[110:111], v[242:243], v[28:29], v[110:111]
	v_pk_fma_f32 v[108:109], v[244:245], v[14:15], v[108:109]
	v_pk_fma_f32 v[110:111], v[244:245], v[30:31], v[110:111]
	v_pk_fma_f32 v[108:109], v[246:247], v[16:17], v[108:109]
	v_pk_fma_f32 v[110:111], v[246:247], v[32:33], v[110:111]
	s_nop 0
	v_add_f32_e32 v2, v108, v109
	v_add_f32_e32 v18, v110, v111
	s_cmp_eq_u32 s33, 0x70
	s_cbranch_scc1 .Lpf_skip_AU
	s_add_i32 s48, s34, 2
	s_cmp_lt_u32 s48, 8
	s_cselect_b64 s[58:59], -1, 0
	v_cndmask_b32_e64 v215, v212, v211, s[58:59]
	s_add_i32 s49, s33, 16
	v_readlane_b32 s40, v215, s49
	s_add_i32 s49, s33, 17
	v_readlane_b32 s41, v215, s49
	s_add_i32 s49, s33, 18
	v_readlane_b32 s42, v215, s49
	s_add_i32 s49, s33, 19
	v_readlane_b32 s43, v215, s49
	s_add_i32 s49, s33, 20
	v_readlane_b32 s44, v215, s49
	s_add_i32 s49, s33, 21
	v_readlane_b32 s45, v215, s49
	s_add_i32 s49, s33, 22
	v_readlane_b32 s46, v215, s49
	s_add_i32 s49, s33, 23
	v_readlane_b32 s47, v215, s49
	v_mad_u32_u24 v153, s41, v202, v138
	v_mad_u32_u24 v152, s40, v202, v138
	global_load_dwordx4 v[50:53], v153, s[78:79] offset:-4
	global_load_dwordx3 v[48:50], v152, s[78:79]
	v_mad_u32_u24 v155, s43, v202, v138
	v_mad_u32_u24 v154, s42, v202, v138
	global_load_dwordx4 v[56:59], v155, s[78:79] offset:-4
	global_load_dwordx3 v[54:56], v154, s[78:79]
	v_mad_u32_u24 v153, s45, v202, v138
	v_mad_u32_u24 v152, s44, v202, v138
	global_load_dwordx4 v[62:65], v153, s[78:79] offset:-4
	global_load_dwordx3 v[60:62], v152, s[78:79]
	v_mad_u32_u24 v155, s47, v202, v138
	v_mad_u32_u24 v154, s46, v202, v138
	global_load_dwordx4 v[78:81], v155, s[78:79] offset:-4
	global_load_dwordx3 v[76:78], v154, s[78:79]

.Lmw1_A:
	s_cmp_lt_u32 s34, 8
	s_cselect_b64 s[2:3], -1, 0
	s_waitcnt vmcnt(8)
	s_waitcnt lgkmcnt(0)
	v_cvt_scalef32_pk32_f32_fp6 v[2:33], v[34:39], 1.0
	v_pk_mul_f32 v[108:109], v[232:233], v[2:3]
	v_pk_mul_f32 v[110:111], v[232:233], v[18:19]
	v_pk_fma_f32 v[108:109], v[234:235], v[4:5], v[108:109]
	v_pk_fma_f32 v[110:111], v[234:235], v[20:21], v[110:111]
	v_pk_fma_f32 v[108:109], v[236:237], v[6:7], v[108:109]
	v_pk_fma_f32 v[110:111], v[236:237], v[22:23], v[110:111]
	v_pk_fma_f32 v[108:109], v[238:239], v[8:9], v[108:109]
	v_pk_fma_f32 v[110:111], v[238:239], v[24:25], v[110:111]
	v_pk_fma_f32 v[108:109], v[240:241], v[10:11], v[108:109]
	v_pk_fma_f32 v[110:111], v[240:241], v[26:27], v[110:111]
	v_pk_fma_f32 v[108:109], v[242:243], v[12:13], v[108:109]
	v_pk_fma_f32 v[110:111], v[242:243], v[28:29], v[110:111]
	v_pk_fma_f32 v[108:109], v[244:245], v[14:15], v[108:109]
	v_pk_fma_f32 v[110:111], v[244:245], v[30:31], v[110:111]
	v_pk_fma_f32 v[108:109], v[246:247], v[16:17], v[108:109]
	v_pk_fma_f32 v[110:111], v[246:247], v[32:33], v[110:111]
	s_nop 0
	v_add_f32_e32 v112, v108, v109
	v_add_f32_e32 v113, v110, v111
	v_cvt_scalef32_pk32_f32_fp6 v[2:33], v[66:71], 1.0
	v_pk_mul_f32 v[108:109], v[232:233], v[2:3]
	v_pk_mul_f32 v[110:111], v[232:233], v[18:19]
	v_pk_fma_f32 v[108:109], v[234:235], v[4:5], v[108:109]
	v_pk_fma_f32 v[110:111], v[234:235], v[20:21], v[110:111]
	v_pk_fma_f32 v[108:109], v[236:237], v[6:7], v[108:109]
	v_pk_fma_f32 v[110:111], v[236:237], v[22:23], v[110:111]
	v_pk_fma_f32 v[108:109], v[238:239], v[8:9], v[108:109]
	v_pk_fma_f32 v[110:111], v[238:239], v[24:25], v[110:111]
	v_pk_fma_f32 v[108:109], v[240:241], v[10:11], v[108:109]
	v_pk_fma_f32 v[110:111], v[240:241], v[26:27], v[110:111]
	v_pk_fma_f32 v[108:109], v[242:243], v[12:13], v[108:109]
	v_pk_fma_f32 v[110:111], v[242:243], v[28:29], v[110:111]
	v_pk_fma_f32 v[108:109], v[244:245], v[14:15], v[108:109]
	v_pk_fma_f32 v[110:111], v[244:245], v[30:31], v[110:111]
	v_pk_fma_f32 v[108:109], v[246:247], v[16:17], v[108:109]
	v_pk_fma_f32 v[110:111], v[246:247], v[32:33], v[110:111]
	s_nop 0
	v_add_f32_e32 v114, v108, v109
	v_add_f32_e32 v115, v110, v111
	v_cvt_scalef32_pk32_f32_fp6 v[2:33], v[98:103], 1.0
	v_pk_mul_f32 v[108:109], v[232:233], v[2:3]
	v_pk_mul_f32 v[110:111], v[232:233], v[18:19]
	v_pk_fma_f32 v[108:109], v[234:235], v[4:5], v[108:109]
	v_pk_fma_f32 v[110:111], v[234:235], v[20:21], v[110:111]
	v_pk_fma_f32 v[108:109], v[236:237], v[6:7], v[108:109]
	v_pk_fma_f32 v[110:111], v[236:237], v[22:23], v[110:111]
	v_pk_fma_f32 v[108:109], v[238:239], v[8:9], v[108:109]
	v_pk_fma_f32 v[110:111], v[238:239], v[24:25], v[110:111]
	v_pk_fma_f32 v[108:109], v[240:241], v[10:11], v[108:109]
	v_pk_fma_f32 v[110:111], v[240:241], v[26:27], v[110:111]
	v_pk_fma_f32 v[108:109], v[242:243], v[12:13], v[108:109]
	v_pk_fma_f32 v[110:111], v[242:243], v[28:29], v[110:111]
	v_pk_fma_f32 v[108:109], v[244:245], v[14:15], v[108:109]
	v_pk_fma_f32 v[110:111], v[244:245], v[30:31], v[110:111]
	v_pk_fma_f32 v[108:109], v[246:247], v[16:17], v[108:109]
	v_pk_fma_f32 v[110:111], v[246:247], v[32:33], v[110:111]
	s_nop 0
	v_add_f32_e32 v116, v108, v109
	v_add_f32_e32 v117, v110, v111
	v_cvt_scalef32_pk32_f32_fp6 v[2:33], v[130:135], 1.0
	v_pk_mul_f32 v[108:109], v[232:233], v[2:3]
	v_pk_mul_f32 v[110:111], v[232:233], v[18:19]
	v_pk_fma_f32 v[108:109], v[234:235], v[4:5], v[108:109]
	v_pk_fma_f32 v[110:111], v[234:235], v[20:21], v[110:111]
	v_pk_fma_f32 v[108:109], v[236:237], v[6:7], v[108:109]
	v_pk_fma_f32 v[110:111], v[236:237], v[22:23], v[110:111]
	v_pk_fma_f32 v[108:109], v[238:239], v[8:9], v[108:109]
	v_pk_fma_f32 v[110:111], v[238:239], v[24:25], v[110:111]
	v_pk_fma_f32 v[108:109], v[240:241], v[10:11], v[108:109]
	v_pk_fma_f32 v[110:111], v[240:241], v[26:27], v[110:111]
	v_pk_fma_f32 v[108:109], v[242:243], v[12:13], v[108:109]
	v_pk_fma_f32 v[110:111], v[242:243], v[28:29], v[110:111]
	v_pk_fma_f32 v[108:109], v[244:245], v[14:15], v[108:109]
	v_pk_fma_f32 v[110:111], v[244:245], v[30:31], v[110:111]
	v_pk_fma_f32 v[108:109], v[246:247], v[16:17], v[108:109]
	v_pk_fma_f32 v[110:111], v[246:247], v[32:33], v[110:111]
	s_nop 0
	v_add_f32_e32 v2, v108, v109
	v_add_f32_e32 v18, v110, v111
	s_cmp_eq_u32 s33, 0x78
	s_cbranch_scc1 .Lpf_skip_AV
	s_add_i32 s48, s34, 2
	s_cmp_lt_u32 s48, 8
	s_cselect_b64 s[58:59], -1, 0
	v_cndmask_b32_e64 v215, v212, v211, s[58:59]
	s_add_i32 s49, s33, 16
	v_readlane_b32 s40, v215, s49
	s_add_i32 s49, s33, 17
	v_readlane_b32 s41, v215, s49
	s_add_i32 s49, s33, 18
	v_readlane_b32 s42, v215, s49
	s_add_i32 s49, s33, 19
	v_readlane_b32 s43, v215, s49
	s_add_i32 s49, s33, 20
	v_readlane_b32 s44, v215, s49
	s_add_i32 s49, s33, 21
	v_readlane_b32 s45, v215, s49
	s_add_i32 s49, s33, 22
	v_readlane_b32 s46, v215, s49
	s_add_i32 s49, s33, 23
	v_readlane_b32 s47, v215, s49
	v_mad_u32_u24 v153, s41, v202, v138
	v_mad_u32_u24 v152, s40, v202, v138
	global_load_dwordx4 v[36:39], v153, s[78:79] offset:-4
	global_load_dwordx3 v[34:36], v152, s[78:79]
	v_mad_u32_u24 v155, s43, v202, v138
	v_mad_u32_u24 v154, s42, v202, v138
	global_load_dwordx4 v[68:71], v155, s[78:79] offset:-4
	global_load_dwordx3 v[66:68], v154, s[78:79]
	v_mad_u32_u24 v153, s45, v202, v138
	v_mad_u32_u24 v152, s44, v202, v138
	global_load_dwordx4 v[100:103], v153, s[78:79] offset:-4
	global_load_dwordx3 v[98:100], v152, s[78:79]
	v_mad_u32_u24 v155, s47, v202, v138
	v_mad_u32_u24 v154, s46, v202, v138
	global_load_dwordx4 v[132:135], v155, s[78:79] offset:-4
	global_load_dwordx3 v[130:132], v154, s[78:79]

.LpB_hdr:
	v_ashrrev_i32_e32 v143, 31, v142
	v_lshlrev_b64 v[164:165], 11, v[142:143]
	v_lshl_add_u64 v[162:163], v[144:145], 0, v[164:165]
	v_lshlrev_b64 v[10:11], 9, v[142:143]
	v_lshl_or_b32 v10, v136, 2, v10
	v_lshl_add_u64 v[18:19], s[82:83], 0, v[10:11]
	v_lshl_add_u64 v[20:21], s[64:65], 0, v[10:11]
	s_mov_b32 s33, 0
	s_mov_b32 s34, 0
	v_mov_b32_e32 v180, 0
	v_mov_b32_e32 v181, v139
	v_mov_b32_e32 v178, 0
	v_mov_b32_e32 v179, v139
	v_mov_b32_e32 v176, 0
	v_mov_b32_e32 v177, v139
	v_mov_b32_e32 v174, 0
	v_mov_b32_e32 v175, v139
	v_mov_b32_e32 v172, 0
	v_mov_b32_e32 v173, v139
	v_mov_b32_e32 v170, 0
	v_mov_b32_e32 v171, v139
	v_mov_b32_e32 v168, 0
	v_mov_b32_e32 v169, v139
	v_mov_b32_e32 v166, 0
	v_mov_b32_e32 v167, v139
	global_load_dword v211, v[18:19], off
	global_load_dword v212, v[18:19], off offset:256
	global_load_dword v213, v[20:21], off sc1
	global_load_dword v214, v[20:21], off offset:256 sc1
	v_and_b32_e32 v3, 64, v182
	v_xor_b32_e32 v2, 1, v182
	v_add_u32_e32 v4, 64, v3
	v_cmp_lt_i32_e64 s[2:3], v2, v4
	v_or_b32_e32 v231, v198, v3
	s_nop 0
	v_cndmask_b32_e64 v2, v182, v2, s[2:3]
	v_lshlrev_b32_e32 v205, 2, v2
	v_xor_b32_e32 v2, 2, v182
	v_cmp_lt_i32_e64 s[2:3], v2, v4
	s_nop 1
	v_cndmask_b32_e64 v2, v182, v2, s[2:3]
	v_lshlrev_b32_e32 v206, 2, v2
	v_xor_b32_e32 v2, 4, v182
	v_cmp_lt_i32_e64 s[2:3], v2, v4
	s_nop 1
	v_cndmask_b32_e64 v2, v182, v2, s[2:3]
	v_lshlrev_b32_e32 v207, 2, v2
	v_xor_b32_e32 v2, 8, v182
	v_cmp_lt_i32_e64 s[2:3], v2, v4
	s_nop 1
	v_cndmask_b32_e64 v2, v182, v2, s[2:3]
	v_lshlrev_b32_e32 v208, 2, v2
	v_xor_b32_e32 v2, 16, v182
	v_cmp_lt_i32_e64 s[2:3], v2, v4
	s_nop 1
	v_cndmask_b32_e64 v2, v182, v2, s[2:3]
	v_lshlrev_b32_e32 v209, 2, v2
	v_xor_b32_e32 v2, 32, v182
	v_cmp_lt_i32_e64 s[2:3], v2, v4
	s_nop 1
	v_cndmask_b32_e64 v2, v182, v2, s[2:3]
	v_lshlrev_b32_e32 v210, 2, v2
	s_waitcnt vmcnt(0)
	s_add_i32 s49, s33, 0
	v_readlane_b32 s40, v211, s49
	s_add_i32 s49, s33, 1
	v_readlane_b32 s41, v211, s49
	s_add_i32 s49, s33, 2
	v_readlane_b32 s42, v211, s49
	s_add_i32 s49, s33, 3
	v_readlane_b32 s43, v211, s49
	s_add_i32 s49, s33, 4
	v_readlane_b32 s44, v211, s49
	s_add_i32 s49, s33, 5
	v_readlane_b32 s45, v211, s49
	s_add_i32 s49, s33, 6
	v_readlane_b32 s46, v211, s49
	s_add_i32 s49, s33, 7
	v_readlane_b32 s47, v211, s49
	v_mad_u32_u24 v153, s41, v202, v138
	v_mad_u32_u24 v152, s40, v202, v138
	global_load_dwordx4 v[36:39], v153, s[80:81] offset:-4
	global_load_dwordx3 v[34:36], v152, s[80:81]
	v_mad_u32_u24 v155, s43, v202, v138
	v_mad_u32_u24 v154, s42, v202, v138
	global_load_dwordx4 v[68:71], v155, s[80:81] offset:-4
	global_load_dwordx3 v[66:68], v154, s[80:81]
	v_mad_u32_u24 v153, s45, v202, v138
	v_mad_u32_u24 v152, s44, v202, v138
	global_load_dwordx4 v[100:103], v153, s[80:81] offset:-4
	global_load_dwordx3 v[98:100], v152, s[80:81]
	v_mad_u32_u24 v155, s47, v202, v138
	v_mad_u32_u24 v154, s46, v202, v138
	global_load_dwordx4 v[132:135], v155, s[80:81] offset:-4
	global_load_dwordx3 v[130:132], v154, s[80:81]
	s_add_i32 s49, s33, 8
	v_readlane_b32 s40, v211, s49
	s_add_i32 s49, s33, 9
	v_readlane_b32 s41, v211, s49
	s_add_i32 s49, s33, 10
	v_readlane_b32 s42, v211, s49
	s_add_i32 s49, s33, 11
	v_readlane_b32 s43, v211, s49
	s_add_i32 s49, s33, 12
	v_readlane_b32 s44, v211, s49
	s_add_i32 s49, s33, 13
	v_readlane_b32 s45, v211, s49
	s_add_i32 s49, s33, 14
	v_readlane_b32 s46, v211, s49
	s_add_i32 s49, s33, 15
	v_readlane_b32 s47, v211, s49
	v_mad_u32_u24 v153, s41, v202, v138
	v_mad_u32_u24 v152, s40, v202, v138
	global_load_dwordx4 v[218:221], v153, s[80:81] offset:-4
	global_load_dwordx3 v[216:218], v152, s[80:81]
	v_mad_u32_u24 v155, s43, v202, v138
	v_mad_u32_u24 v154, s42, v202, v138
	global_load_dwordx4 v[226:229], v155, s[80:81] offset:-4
	global_load_dwordx3 v[224:226], v154, s[80:81]
	v_mad_u32_u24 v153, s45, v202, v138
	v_mad_u32_u24 v152, s44, v202, v138
	global_load_dwordx4 v[234:237], v153, s[80:81] offset:-4
	global_load_dwordx3 v[232:234], v152, s[80:81]
	v_mad_u32_u24 v155, s47, v202, v138
	v_mad_u32_u24 v154, s46, v202, v138
	global_load_dwordx4 v[242:245], v155, s[80:81] offset:-4
	global_load_dwordx3 v[240:242], v154, s[80:81]
.LpB_kb:
	s_waitcnt vmcnt(8)
	s_cmp_lt_u32 s34, 8
	s_cselect_b64 s[2:3], -1, 0
	v_and_or_b32 v5, s33, 56, v231
	v_lshlrev_b32_e32 v5, 2, v5
	v_cndmask_b32_e64 v2, v214, v213, s[2:3]
	s_nop 0
	ds_bpermute_b32 v107, v5, v2
	s_waitcnt lgkmcnt(0)
	s_nop 0
	v_readlane_b32 s2, v107, 0
	v_readlane_b32 s14, v107, 1
	v_readlane_b32 s16, v107, 2
	v_readlane_b32 s18, v107, 3
	v_readlane_b32 s20, v107, 4
	v_readlane_b32 s22, v107, 5
	v_readlane_b32 s24, v107, 6
	v_readlane_b32 s26, v107, 7
	v_cvt_scalef32_pk32_f32_fp6 v[2:33], v[34:39], 1.0
	v_pk_fma_f32 v[178:179], v[2:3], s[2:3], v[178:179] op_sel_hi:[1,0,1]
	v_pk_fma_f32 v[176:177], v[4:5], s[2:3], v[176:177] op_sel_hi:[1,0,1]
	v_pk_fma_f32 v[174:175], v[6:7], s[2:3], v[174:175] op_sel_hi:[1,0,1]
	v_pk_fma_f32 v[172:173], v[8:9], s[2:3], v[172:173] op_sel_hi:[1,0,1]
	v_pk_fma_f32 v[170:171], v[10:11], s[2:3], v[170:171] op_sel_hi:[1,0,1]
	v_pk_fma_f32 v[168:169], v[12:13], s[2:3], v[168:169] op_sel_hi:[1,0,1]
	v_pk_fma_f32 v[166:167], v[14:15], s[2:3], v[166:167] op_sel_hi:[1,0,1]
	v_pk_fma_f32 v[180:181], v[16:17], s[2:3], v[180:181] op_sel_hi:[1,0,1]
	v_pk_fma_f32 v[178:179], v[18:19], s[14:15], v[178:179] op_sel_hi:[1,0,1]
	v_pk_fma_f32 v[176:177], v[20:21], s[14:15], v[176:177] op_sel_hi:[1,0,1]
	v_pk_fma_f32 v[174:175], v[22:23], s[14:15], v[174:175] op_sel_hi:[1,0,1]
	v_pk_fma_f32 v[172:173], v[24:25], s[14:15], v[172:173] op_sel_hi:[1,0,1]
	v_pk_fma_f32 v[170:171], v[26:27], s[14:15], v[170:171] op_sel_hi:[1,0,1]
	v_pk_fma_f32 v[168:169], v[28:29], s[14:15], v[168:169] op_sel_hi:[1,0,1]
	v_pk_fma_f32 v[166:167], v[30:31], s[14:15], v[166:167] op_sel_hi:[1,0,1]
	v_pk_fma_f32 v[180:181], v[32:33], s[14:15], v[180:181] op_sel_hi:[1,0,1]
	v_cvt_scalef32_pk32_f32_fp6 v[2:33], v[66:71], 1.0
	v_pk_fma_f32 v[178:179], v[2:3], s[16:17], v[178:179] op_sel_hi:[1,0,1]
	v_pk_fma_f32 v[176:177], v[4:5], s[16:17], v[176:177] op_sel_hi:[1,0,1]
	v_pk_fma_f32 v[174:175], v[6:7], s[16:17], v[174:175] op_sel_hi:[1,0,1]
	v_pk_fma_f32 v[172:173], v[8:9], s[16:17], v[172:173] op_sel_hi:[1,0,1]
	v_pk_fma_f32 v[170:171], v[10:11], s[16:17], v[170:171] op_sel_hi:[1,0,1]
	v_pk_fma_f32 v[168:169], v[12:13], s[16:17], v[168:169] op_sel_hi:[1,0,1]
	v_pk_fma_f32 v[166:167], v[14:15], s[16:17], v[166:167] op_sel_hi:[1,0,1]
	v_pk_fma_f32 v[180:181], v[16:17], s[16:17], v[180:181] op_sel_hi:[1,0,1]
	v_pk_fma_f32 v[178:179], v[18:19], s[18:19], v[178:179] op_sel_hi:[1,0,1]
	v_pk_fma_f32 v[176:177], v[20:21], s[18:19], v[176:177] op_sel_hi:[1,0,1]
	v_pk_fma_f32 v[174:175], v[22:23], s[18:19], v[174:175] op_sel_hi:[1,0,1]
	v_pk_fma_f32 v[172:173], v[24:25], s[18:19], v[172:173] op_sel_hi:[1,0,1]
	v_pk_fma_f32 v[170:171], v[26:27], s[18:19], v[170:171] op_sel_hi:[1,0,1]
	v_pk_fma_f32 v[168:169], v[28:29], s[18:19], v[168:169] op_sel_hi:[1,0,1]
	v_pk_fma_f32 v[166:167], v[30:31], s[18:19], v[166:167] op_sel_hi:[1,0,1]
	v_pk_fma_f32 v[180:181], v[32:33], s[18:19], v[180:181] op_sel_hi:[1,0,1]
	v_cvt_scalef32_pk32_f32_fp6 v[2:33], v[98:103], 1.0
	v_pk_fma_f32 v[178:179], v[2:3], s[20:21], v[178:179] op_sel_hi:[1,0,1]
	v_pk_fma_f32 v[176:177], v[4:5], s[20:21], v[176:177] op_sel_hi:[1,0,1]
	v_pk_fma_f32 v[174:175], v[6:7], s[20:21], v[174:175] op_sel_hi:[1,0,1]
	v_pk_fma_f32 v[172:173], v[8:9], s[20:21], v[172:173] op_sel_hi:[1,0,1]
	v_pk_fma_f32 v[170:171], v[10:11], s[20:21], v[170:171] op_sel_hi:[1,0,1]
	v_pk_fma_f32 v[168:169], v[12:13], s[20:21], v[168:169] op_sel_hi:[1,0,1]
	v_pk_fma_f32 v[166:167], v[14:15], s[20:21], v[166:167] op_sel_hi:[1,0,1]
	v_pk_fma_f32 v[180:181], v[16:17], s[20:21], v[180:181] op_sel_hi:[1,0,1]
	v_pk_fma_f32 v[178:179], v[18:19], s[22:23], v[178:179] op_sel_hi:[1,0,1]
	v_pk_fma_f32 v[176:177], v[20:21], s[22:23], v[176:177] op_sel_hi:[1,0,1]
	v_pk_fma_f32 v[174:175], v[22:23], s[22:23], v[174:175] op_sel_hi:[1,0,1]
	v_pk_fma_f32 v[172:173], v[24:25], s[22:23], v[172:173] op_sel_hi:[1,0,1]
	v_pk_fma_f32 v[170:171], v[26:27], s[22:23], v[170:171] op_sel_hi:[1,0,1]
	v_pk_fma_f32 v[168:169], v[28:29], s[22:23], v[168:169] op_sel_hi:[1,0,1]
	v_pk_fma_f32 v[166:167], v[30:31], s[22:23], v[166:167] op_sel_hi:[1,0,1]
	v_pk_fma_f32 v[180:181], v[32:33], s[22:23], v[180:181] op_sel_hi:[1,0,1]
	v_cvt_scalef32_pk32_f32_fp6 v[2:33], v[130:135], 1.0
	s_cmp_eq_u32 s33, 0x70
	s_cbranch_scc1 .Lpf_skip_BV
	s_add_i32 s48, s34, 2
	s_cmp_lt_u32 s48, 8
	s_cselect_b64 s[58:59], -1, 0
	v_cndmask_b32_e64 v215, v212, v211, s[58:59]
	s_add_i32 s49, s33, 16
	v_readlane_b32 s40, v215, s49
	s_add_i32 s49, s33, 17
	v_readlane_b32 s41, v215, s49
	s_add_i32 s49, s33, 18
	v_readlane_b32 s42, v215, s49
	s_add_i32 s49, s33, 19
	v_readlane_b32 s43, v215, s49
	s_add_i32 s49, s33, 20
	v_readlane_b32 s44, v215, s49
	s_add_i32 s49, s33, 21
	v_readlane_b32 s45, v215, s49
	s_add_i32 s49, s33, 22
	v_readlane_b32 s46, v215, s49
	s_add_i32 s49, s33, 23
	v_readlane_b32 s47, v215, s49
	v_mad_u32_u24 v153, s41, v202, v138
	v_mad_u32_u24 v152, s40, v202, v138
	global_load_dwordx4 v[36:39], v153, s[80:81] offset:-4
	global_load_dwordx3 v[34:36], v152, s[80:81]
	v_mad_u32_u24 v155, s43, v202, v138
	v_mad_u32_u24 v154, s42, v202, v138
	global_load_dwordx4 v[68:71], v155, s[80:81] offset:-4
	global_load_dwordx3 v[66:68], v154, s[80:81]
	v_mad_u32_u24 v153, s45, v202, v138
	v_mad_u32_u24 v152, s44, v202, v138
	global_load_dwordx4 v[100:103], v153, s[80:81] offset:-4
	global_load_dwordx3 v[98:100], v152, s[80:81]
	v_mad_u32_u24 v155, s47, v202, v138
	v_mad_u32_u24 v154, s46, v202, v138
	global_load_dwordx4 v[132:135], v155, s[80:81] offset:-4
	global_load_dwordx3 v[130:132], v154, s[80:81]

.Lmw1_B:
	s_cmp_lt_u32 s34, 8
	s_cselect_b64 s[2:3], -1, 0
	v_and_or_b32 v5, s33, 56, v231
	v_lshlrev_b32_e32 v5, 2, v5
	v_cndmask_b32_e64 v2, v214, v213, s[2:3]
	s_nop 0
	ds_bpermute_b32 v107, v5, v2
	s_waitcnt lgkmcnt(0)
	s_nop 0
	v_readlane_b32 s2, v107, 0
	v_readlane_b32 s14, v107, 1
	v_readlane_b32 s16, v107, 2
	v_readlane_b32 s18, v107, 3
	v_readlane_b32 s20, v107, 4
	v_readlane_b32 s22, v107, 5
	v_readlane_b32 s24, v107, 6
	v_readlane_b32 s26, v107, 7
	v_cvt_scalef32_pk32_f32_fp6 v[2:33], v[216:221], 1.0
	v_pk_fma_f32 v[178:179], v[2:3], s[2:3], v[178:179] op_sel_hi:[1,0,1]
	v_pk_fma_f32 v[176:177], v[4:5], s[2:3], v[176:177] op_sel_hi:[1,0,1]
	v_pk_fma_f32 v[174:175], v[6:7], s[2:3], v[174:175] op_sel_hi:[1,0,1]
	v_pk_fma_f32 v[172:173], v[8:9], s[2:3], v[172:173] op_sel_hi:[1,0,1]
	v_pk_fma_f32 v[170:171], v[10:11], s[2:3], v[170:171] op_sel_hi:[1,0,1]
	v_pk_fma_f32 v[168:169], v[12:13], s[2:3], v[168:169] op_sel_hi:[1,0,1]
	v_pk_fma_f32 v[166:167], v[14:15], s[2:3], v[166:167] op_sel_hi:[1,0,1]
	v_pk_fma_f32 v[180:181], v[16:17], s[2:3], v[180:181] op_sel_hi:[1,0,1]
	v_pk_fma_f32 v[178:179], v[18:19], s[14:15], v[178:179] op_sel_hi:[1,0,1]
	v_pk_fma_f32 v[176:177], v[20:21], s[14:15], v[176:177] op_sel_hi:[1,0,1]
	v_pk_fma_f32 v[174:175], v[22:23], s[14:15], v[174:175] op_sel_hi:[1,0,1]
	v_pk_fma_f32 v[172:173], v[24:25], s[14:15], v[172:173] op_sel_hi:[1,0,1]
	v_pk_fma_f32 v[170:171], v[26:27], s[14:15], v[170:171] op_sel_hi:[1,0,1]
	v_pk_fma_f32 v[168:169], v[28:29], s[14:15], v[168:169] op_sel_hi:[1,0,1]
	v_pk_fma_f32 v[166:167], v[30:31], s[14:15], v[166:167] op_sel_hi:[1,0,1]
	v_pk_fma_f32 v[180:181], v[32:33], s[14:15], v[180:181] op_sel_hi:[1,0,1]
	v_cvt_scalef32_pk32_f32_fp6 v[2:33], v[224:229], 1.0
	v_pk_fma_f32 v[178:179], v[2:3], s[16:17], v[178:179] op_sel_hi:[1,0,1]
	v_pk_fma_f32 v[176:177], v[4:5], s[16:17], v[176:177] op_sel_hi:[1,0,1]
	v_pk_fma_f32 v[174:175], v[6:7], s[16:17], v[174:175] op_sel_hi:[1,0,1]
	v_pk_fma_f32 v[172:173], v[8:9], s[16:17], v[172:173] op_sel_hi:[1,0,1]
	v_pk_fma_f32 v[170:171], v[10:11], s[16:17], v[170:171] op_sel_hi:[1,0,1]
	v_pk_fma_f32 v[168:169], v[12:13], s[16:17], v[168:169] op_sel_hi:[1,0,1]
	v_pk_fma_f32 v[166:167], v[14:15], s[16:17], v[166:167] op_sel_hi:[1,0,1]
	v_pk_fma_f32 v[180:181], v[16:17], s[16:17], v[180:181] op_sel_hi:[1,0,1]
	v_pk_fma_f32 v[178:179], v[18:19], s[18:19], v[178:179] op_sel_hi:[1,0,1]
	v_pk_fma_f32 v[176:177], v[20:21], s[18:19], v[176:177] op_sel_hi:[1,0,1]
	v_pk_fma_f32 v[174:175], v[22:23], s[18:19], v[174:175] op_sel_hi:[1,0,1]
	v_pk_fma_f32 v[172:173], v[24:25], s[18:19], v[172:173] op_sel_hi:[1,0,1]
	v_pk_fma_f32 v[170:171], v[26:27], s[18:19], v[170:171] op_sel_hi:[1,0,1]
	v_pk_fma_f32 v[168:169], v[28:29], s[18:19], v[168:169] op_sel_hi:[1,0,1]
	v_pk_fma_f32 v[166:167], v[30:31], s[18:19], v[166:167] op_sel_hi:[1,0,1]
	v_pk_fma_f32 v[180:181], v[32:33], s[18:19], v[180:181] op_sel_hi:[1,0,1]
	v_cvt_scalef32_pk32_f32_fp6 v[2:33], v[232:237], 1.0
	v_pk_fma_f32 v[178:179], v[2:3], s[20:21], v[178:179] op_sel_hi:[1,0,1]
	v_pk_fma_f32 v[176:177], v[4:5], s[20:21], v[176:177] op_sel_hi:[1,0,1]
	v_pk_fma_f32 v[174:175], v[6:7], s[20:21], v[174:175] op_sel_hi:[1,0,1]
	v_pk_fma_f32 v[172:173], v[8:9], s[20:21], v[172:173] op_sel_hi:[1,0,1]
	v_pk_fma_f32 v[170:171], v[10:11], s[20:21], v[170:171] op_sel_hi:[1,0,1]
	v_pk_fma_f32 v[168:169], v[12:13], s[20:21], v[168:169] op_sel_hi:[1,0,1]
	v_pk_fma_f32 v[166:167], v[14:15], s[20:21], v[166:167] op_sel_hi:[1,0,1]
	v_pk_fma_f32 v[180:181], v[16:17], s[20:21], v[180:181] op_sel_hi:[1,0,1]
	v_pk_fma_f32 v[178:179], v[18:19], s[22:23], v[178:179] op_sel_hi:[1,0,1]
	v_pk_fma_f32 v[176:177], v[20:21], s[22:23], v[176:177] op_sel_hi:[1,0,1]
	v_pk_fma_f32 v[174:175], v[22:23], s[22:23], v[174:175] op_sel_hi:[1,0,1]
	v_pk_fma_f32 v[172:173], v[24:25], s[22:23], v[172:173] op_sel_hi:[1,0,1]
	v_pk_fma_f32 v[170:171], v[26:27], s[22:23], v[170:171] op_sel_hi:[1,0,1]
	v_pk_fma_f32 v[168:169], v[28:29], s[22:23], v[168:169] op_sel_hi:[1,0,1]
	v_pk_fma_f32 v[166:167], v[30:31], s[22:23], v[166:167] op_sel_hi:[1,0,1]
	v_pk_fma_f32 v[180:181], v[32:33], s[22:23], v[180:181] op_sel_hi:[1,0,1]
	v_cvt_scalef32_pk32_f32_fp6 v[2:33], v[240:245], 1.0
	s_cmp_eq_u32 s33, 0x78
	s_cbranch_scc1 .Lpf_skip_BP
	s_add_i32 s48, s34, 2
	s_cmp_lt_u32 s48, 8
	s_cselect_b64 s[58:59], -1, 0
	v_cndmask_b32_e64 v215, v212, v211, s[58:59]
	s_add_i32 s49, s33, 16
	v_readlane_b32 s40, v215, s49
	s_add_i32 s49, s33, 17
	v_readlane_b32 s41, v215, s49
	s_add_i32 s49, s33, 18
	v_readlane_b32 s42, v215, s49
	s_add_i32 s49, s33, 19
	v_readlane_b32 s43, v215, s49
	s_add_i32 s49, s33, 20
	v_readlane_b32 s44, v215, s49
	s_add_i32 s49, s33, 21
	v_readlane_b32 s45, v215, s49
	s_add_i32 s49, s33, 22
	v_readlane_b32 s46, v215, s49
	s_add_i32 s49, s33, 23
	v_readlane_b32 s47, v215, s49
	v_mad_u32_u24 v153, s41, v202, v138
	v_mad_u32_u24 v152, s40, v202, v138
	global_load_dwordx4 v[218:221], v153, s[80:81] offset:-4
	global_load_dwordx3 v[216:218], v152, s[80:81]
	v_mad_u32_u24 v155, s43, v202, v138
	v_mad_u32_u24 v154, s42, v202, v138
	global_load_dwordx4 v[226:229], v155, s[80:81] offset:-4
	global_load_dwordx3 v[224:226], v154, s[80:81]
	v_mad_u32_u24 v153, s45, v202, v138
	v_mad_u32_u24 v152, s44, v202, v138
	global_load_dwordx4 v[234:237], v153, s[80:81] offset:-4
	global_load_dwordx3 v[232:234], v152, s[80:81]
	v_mad_u32_u24 v155, s47, v202, v138
	v_mad_u32_u24 v154, s46, v202, v138
	global_load_dwordx4 v[242:245], v155, s[80:81] offset:-4
	global_load_dwordx3 v[240:242], v154, s[80:81]
